# fast-path blocks run at raised priority from their start (max chain and first exp stage included), not only from the first PV MFMA
# speedup vs baseline: 1.0029x; 1.0029x over previous
; #define LAS __attribute__((address_space(3)))
; __device__ __forceinline__ f32x16 mfma32(bf16x8 a, bf16x8 b, f32x16 c) { return __builtin_amdgcn_mfma_f32_32x32x16_bf16(a, b, c, 0, 0, 0); }
; template <int MODE, int DK, bool PASS2> ...
;     ...
;                     const LAS unsigned char* vb = lds + F_VB0 + buf * F_VBS + ql * 144 + g * 16;
;                     __builtin_amdgcn_s_setprio(1);
; #pragma unroll
;                     for (int db = 0; db < 4; ++db)
; #pragma unroll
;                         for (int k2 = 0; k2 < 4; ++k2) {
;                             const bf16x8 vf = *(const LAS bf16x8*)(vb + db * 32 * 144 + k2 * 32);
;                             O[db] = mfma32(vf, pf[k2], O[db]);
;                             if (k2 == 3 && (db & 1)) __builtin_amdgcn_sched_barrier(0);
;                         }
;                     __builtin_amdgcn_s_setprio(0);
;                     if (MODE == M_FOX) {
;                         if (has) { const float cn = cg2[jn * 64 + 63]; dead = __builtin_amdgcn_ballot_w64(!((qnb - cn) - m_run < -160.0f)) == 0ull; }
.Lfast_fox:
	s_setprio 1
	s_mul_i32 s98, s86, 0x4800
	v_add_u32_e32 v252, s98, v231
	ds_read_b128 v[240:243], v252 offset:34816
	ds_read_b128 v[244:247], v252 offset:39424
	ds_read_b128 v[248:251], v252 offset:44032
	s_and_b64 vcc, exec, s[10:11]
	s_cbranch_vccnz .Lfast_fox_noload
	s_add_i32 s24, s87, 0xffffff81
	s_lshl_b64 s[52:53], s[24:25], 2
	s_add_u32 s52, s36, s52
	s_addc_u32 s53, s37, s53
	global_load_dword v145, v3, s[52:53] offset:252

; template <int MODE, int DK, bool PASS2> ...
;     ...
;                     float ps0 = 0.f, ps1 = 0.f;
; #pragma unroll
;                     for (int r = 0; r < 16; ++r) {
;                         s0[r] = fexp2(__builtin_fmaf(s0[r], sl2, nm)); s1[r] = fexp2(__builtin_fmaf(s1[r], sl2, nm));
;                         ps0 += s0[r]; ps1 += s1[r];
;                     }
;                     l_run = l_run * alpha + (ps0 + ps1);
;                     if (__builtin_amdgcn_ballot_w64(alpha != 1.0f) != 0ull) {
; #pragma unroll
;                         for (int db = 0; db < 4; ++db)
; #pragma unroll
;                             for (int r = 0; r < 16; ++r) O[db][r] *= alpha;
;                     }
;                 } else {
; #pragma unroll
;                     for (int r = 0; r < 16; ++r) { s0[r] *= sl2; s1[r] *= sl2; }
;                     if (need_bias || need_causal || need_win) {
; #pragma unroll
;                         for (int i = 0; i < 32; ++i) {
;                             const int s = kv0 + (i >> 3) * 16 + 8 * g + (i & 7);
;                             const int dist = t_lane - ((MODE == M_CMP) ? 16 * s + 31 : s);
;                             float v = (i < 16) ? s0[i & 15] : s1[i & 15];
;                             if (need_bias) { const int di = dist < 0 ? 0 : (dist > 128 ? 128 : dist); v += tb[di]; }
;                             bool msk = dist < 0;
;                             if (MODE == M_WIN) msk = msk || dist >= 512;
;                             if (msk) v = NEG;
;                             if (i < 16) s0[i & 15] = v; else s1[i & 15] = v;
;                             if ((i & 7) == 7) __builtin_amdgcn_sched_barrier(0);
;                         }
;                     }
;                     if (MODE == M_SLC) {
;                         if (!selbit) {
; #pragma unroll
;                             for (int r = 0; r < 16; ++r) { s0[r] = NEG; s1[r] = NEG; }
;                         }
;                     }
;                     if (!PASS2) {
;                         float mx = fmaxf(s0[0], s1[0]);
; #pragma unroll
;                         for (int r = 1; r < 16; ++r) mx = fmax3(mx, s0[r], s1[r]);
;                         mx = xhalf_max(mx);
;                         const float mn = (mx > m_run + 8.0f) ? mx : m_run;
;                         const float alpha = fexp2(m_run - mn);
;                         m_run = mn;
.Lfast_fox_norescale:
	v_fma_f32 v118, v98, s83, -v4
	v_fma_f32 v119, v99, s83, -v4
	v_exp_f32_e32 v6, v118
	v_exp_f32_e32 v7, v119
	v_fma_f32 v120, v100, s83, -v4
	v_fma_f32 v121, v101, s83, -v4
	v_exp_f32_e32 v8, v120
	v_exp_f32_e32 v9, v121
	v_add_f32_e32 v122, v6, v7
	v_fma_f32 v118, v102, s83, -v4
	v_fma_f32 v119, v103, s83, -v4
	v_exp_f32_e32 v114, v118
	v_exp_f32_e32 v115, v119
	v_cvt_pk_bf16_f32 v98, v6, v7
	v_add_f32_e32 v122, v122, v8
	v_fma_f32 v120, v104, s83, -v4
	v_add_f32_e32 v122, v122, v9
	v_fma_f32 v121, v105, s83, -v4
	v_exp_f32_e32 v116, v120
	v_exp_f32_e32 v117, v121
	v_cvt_pk_bf16_f32 v99, v8, v9
	v_add_f32_e32 v122, v122, v114
	v_add_f32_e32 v122, v122, v115
	v_cvt_pk_bf16_f32 v100, v114, v115
	v_add_f32_e32 v122, v122, v116
	v_add_f32_e32 v122, v122, v117
	v_cvt_pk_bf16_f32 v101, v116, v117
	v_fma_f32 v118, v106, s83, -v4
	v_fma_f32 v119, v107, s83, -v4
	s_waitcnt lgkmcnt(2)
	v_mfma_f32_32x32x16_bf16 v[66:81], v[240:243], v[98:101], v[66:81]
	v_exp_f32_e32 v6, v118
	v_exp_f32_e32 v7, v119
	v_fma_f32 v120, v108, s83, -v4
	v_fma_f32 v121, v109, s83, -v4
	v_exp_f32_e32 v8, v120
	v_exp_f32_e32 v9, v121
	s_waitcnt lgkmcnt(1)
	v_mfma_f32_32x32x16_bf16 v[50:65], v[244:247], v[98:101], v[50:65]
	ds_read_b128 v[240:243], v252 offset:48640
	v_add_f32_e32 v122, v122, v6
	v_fma_f32 v118, v110, s83, -v4
	v_add_f32_e32 v122, v122, v7
	v_fma_f32 v119, v111, s83, -v4
	v_exp_f32_e32 v114, v118
	v_exp_f32_e32 v115, v119
	s_waitcnt lgkmcnt(1)
	v_mfma_f32_32x32x16_bf16 v[34:49], v[248:251], v[98:101], v[34:49]
	ds_read_b128 v[244:247], v252 offset:34848
	v_cvt_pk_bf16_f32 v106, v6, v7
	v_add_f32_e32 v122, v122, v8
	v_fma_f32 v120, v112, s83, -v4
	v_add_f32_e32 v122, v122, v9
	v_fma_f32 v121, v113, s83, -v4
	v_exp_f32_e32 v116, v120
	s_waitcnt lgkmcnt(1)
	v_mfma_f32_32x32x16_bf16 v[18:33], v[240:243], v[98:101], v[18:33]
	ds_read_b128 v[248:251], v252 offset:39456
	v_exp_f32_e32 v117, v121
	v_cvt_pk_bf16_f32 v107, v8, v9
	v_add_f32_e32 v122, v122, v114
	v_add_f32_e32 v122, v122, v115
	v_cvt_pk_bf16_f32 v108, v114, v115
	v_add_f32_e32 v122, v122, v116
	v_add_f32_e32 v122, v122, v117
	v_cvt_pk_bf16_f32 v109, v116, v117
	v_fma_f32 v118, v82, s83, -v4
	v_fma_f32 v119, v83, s83, -v4
	s_waitcnt lgkmcnt(1)
	v_mfma_f32_32x32x16_bf16 v[66:81], v[244:247], v[106:109], v[66:81]
	ds_read_b128 v[240:243], v252 offset:44064
	v_exp_f32_e32 v6, v118
	v_exp_f32_e32 v7, v119
	v_fma_f32 v120, v84, s83, -v4
	v_fma_f32 v121, v85, s83, -v4
	v_exp_f32_e32 v8, v120
	v_exp_f32_e32 v9, v121
	s_waitcnt lgkmcnt(1)
	v_mfma_f32_32x32x16_bf16 v[50:65], v[248:251], v[106:109], v[50:65]
	ds_read_b128 v[244:247], v252 offset:48672
	v_add_f32_e32 v123, v6, v7
	v_fma_f32 v118, v86, s83, -v4
	v_fma_f32 v119, v87, s83, -v4
	v_exp_f32_e32 v114, v118
	v_exp_f32_e32 v115, v119
	v_cvt_pk_bf16_f32 v82, v6, v7
	s_waitcnt lgkmcnt(1)
	v_mfma_f32_32x32x16_bf16 v[34:49], v[240:243], v[106:109], v[34:49]
	ds_read_b128 v[248:251], v252 offset:34880
	v_add_f32_e32 v123, v123, v8
	v_fma_f32 v120, v88, s83, -v4
	v_add_f32_e32 v123, v123, v9
	v_fma_f32 v121, v89, s83, -v4
	v_exp_f32_e32 v116, v120
	v_exp_f32_e32 v117, v121
	s_waitcnt lgkmcnt(1)
	v_mfma_f32_32x32x16_bf16 v[18:33], v[244:247], v[106:109], v[18:33]
	ds_read_b128 v[240:243], v252 offset:39488
	v_cvt_pk_bf16_f32 v83, v8, v9
	v_add_f32_e32 v123, v123, v114
	v_add_f32_e32 v123, v123, v115
	v_cvt_pk_bf16_f32 v84, v114, v115
	v_add_f32_e32 v123, v123, v116
	v_add_f32_e32 v123, v123, v117
	v_cvt_pk_bf16_f32 v85, v116, v117
	v_fma_f32 v118, v90, s83, -v4
	v_fma_f32 v119, v91, s83, -v4
	s_waitcnt lgkmcnt(1)
	v_mfma_f32_32x32x16_bf16 v[66:81], v[248:251], v[82:85], v[66:81]
	ds_read_b128 v[244:247], v252 offset:44096
	v_exp_f32_e32 v6, v118
	v_exp_f32_e32 v7, v119
	v_fma_f32 v120, v92, s83, -v4
	v_fma_f32 v121, v93, s83, -v4
	v_exp_f32_e32 v8, v120
	v_exp_f32_e32 v9, v121
	s_waitcnt lgkmcnt(1)
	v_mfma_f32_32x32x16_bf16 v[50:65], v[240:243], v[82:85], v[50:65]
	ds_read_b128 v[248:251], v252 offset:48704
	v_add_f32_e32 v123, v123, v6
	v_fma_f32 v118, v94, s83, -v4
	v_add_f32_e32 v123, v123, v7
	v_fma_f32 v119, v95, s83, -v4
	v_exp_f32_e32 v114, v118
	v_exp_f32_e32 v115, v119
	s_waitcnt lgkmcnt(1)
	v_mfma_f32_32x32x16_bf16 v[34:49], v[244:247], v[82:85], v[34:49]
	ds_read_b128 v[240:243], v252 offset:34912
	v_cvt_pk_bf16_f32 v90, v6, v7
	v_add_f32_e32 v123, v123, v8
	v_fma_f32 v120, v96, s83, -v4
	v_add_f32_e32 v123, v123, v9
	v_fma_f32 v121, v97, s83, -v4
	v_exp_f32_e32 v116, v120
	s_waitcnt lgkmcnt(1)
	v_mfma_f32_32x32x16_bf16 v[18:33], v[248:251], v[82:85], v[18:33]
	ds_read_b128 v[244:247], v252 offset:39520
	v_exp_f32_e32 v117, v121
	v_cvt_pk_bf16_f32 v91, v8, v9
	v_add_f32_e32 v123, v123, v114
	v_add_f32_e32 v123, v123, v115
	v_cvt_pk_bf16_f32 v92, v114, v115
	v_add_f32_e32 v123, v123, v116
	v_add_f32_e32 v123, v123, v117
	v_cvt_pk_bf16_f32 v93, v116, v117
	v_add_f32_e32 v5, v122, v123
	s_waitcnt lgkmcnt(1)
	v_mfma_f32_32x32x16_bf16 v[66:81], v[240:243], v[90:93], v[66:81]
	ds_read_b128 v[248:251], v252 offset:44128
	v_fmac_f32_e32 v5, v238, v2
	s_waitcnt lgkmcnt(1)
	v_mfma_f32_32x32x16_bf16 v[50:65], v[244:247], v[90:93], v[50:65]
	ds_read_b128 v[240:243], v252 offset:48736
	s_waitcnt lgkmcnt(1)
	v_mfma_f32_32x32x16_bf16 v[34:49], v[248:251], v[90:93], v[34:49]
	s_waitcnt lgkmcnt(0)
	v_mfma_f32_32x32x16_bf16 v[18:33], v[240:243], v[90:93], v[18:33]
	s_setprio 0
	s_and_b64 vcc, exec, s[10:11]
	s_cbranch_vccnz .Lpostpv_fox
	s_waitcnt vmcnt(0)
	v_mov_b32_e32 v2, v145
	s_branch .Lfox_cn_ready
	s_branch .Lpostpv_fox

; __device__ __forceinline__ float fexp2(float x) { return __builtin_amdgcn_exp2f(x); }
; __device__ __forceinline__ float fmax3(float a, float b, float c) { float d; asm("v_max3_f32 %0, %1, %2, %3" : "=v"(d) : "v"(a), "v"(b), "v"(c)); return d; }
; template <int MODE, int DK, bool PASS2> ...
;     ...
;                     float mx = fmaxf(s0[0], s1[0]);
; #pragma unroll
;                     for (int r = 1; r < 16; ++r) mx = fmax3(mx, s0[r], s1[r]);
;                     if (MODE == M_SLC) mx = selbit ? mx : NEG;
;                     mx = xhalf_max(mx);
;                     const float mxs = mx * sl2;
;                     const float mn = (mxs > m_run + 8.0f) ? mxs : m_run;
;                     const float alpha = fexp2(m_run - mn);
;                     m_run = mn;
;                     float nm = -mn;
;                     if (MODE == M_SLC) nm = selbit ? nm : -__builtin_inff();
;                     float ps0 = 0.f, ps1 = 0.f;
; #pragma unroll
;                     for (int r = 0; r < 16; ++r) {
;                         s0[r] = fexp2(__builtin_fmaf(s0[r], sl2, nm)); s1[r] = fexp2(__builtin_fmaf(s1[r], sl2, nm));
;                         ps0 += s0[r]; ps1 += s1[r];
;                     }
;                     l_run = l_run * alpha + (ps0 + ps1);
;                     if (__builtin_amdgcn_ballot_w64(alpha != 1.0f) != 0ull) {
; #pragma unroll
;                         for (int db = 0; db < 4; ++db)
; #pragma unroll
;                             for (int r = 0; r < 16; ++r) O[db][r] *= alpha;
;                     }
.Lfast_diff:
	s_setprio 1
	s_mul_i32 s98, s58, 0x4800
	v_add_u32_e32 v210, s98, v201
	ds_read_b128 v[212:215], v210 offset:34816
	ds_read_b128 v[216:219], v210 offset:39424
	ds_read_b128 v[220:223], v210 offset:44032
	ds_read_b128 v[224:227], v210 offset:48640
	ds_read_b128 v[228:231], v210 offset:34848
	ds_read_b128 v[232:235], v210 offset:39456
	v_max_f32_e32 v160, v82, v83
	v_max_f32_e32 v161, v98, v99
	v_max3_f32 v160, v160, v84, v85
	v_max3_f32 v161, v161, v100, v101
	v_max3_f32 v160, v160, v86, v87
	v_max3_f32 v161, v161, v102, v103
	v_max3_f32 v160, v160, v88, v89
	v_max3_f32 v161, v161, v104, v105
	v_max3_f32 v160, v160, v90, v91
	v_max3_f32 v161, v161, v106, v107
	v_max3_f32 v160, v160, v92, v93
	v_max3_f32 v161, v161, v108, v109
	v_max3_f32 v160, v160, v94, v95
	v_max3_f32 v161, v161, v110, v111
	v_max3_f32 v160, v160, v96, v97
	v_max3_f32 v161, v161, v112, v113
	v_max_f32_e32 v160, v160, v161
	v_mov_b32_e32 v161, v160
	s_nop 1
	v_permlane32_swap_b32_e32 v160, v161
	v_max_f32_e32 v160, v160, v161
	v_mul_f32_e32 v160, 0x3e38aa3b, v160
	v_cmp_gt_f32_e32 vcc, v160, v208
	s_nop 1
	v_cndmask_b32_e32 v207, v178, v160, vcc
	v_sub_f32_e32 v161, v178, v207
	v_exp_f32_e32 v178, v161
	s_nop 0
	v_cmp_neq_f32_e32 vcc, 1.0, v178
	s_cbranch_vccz .Lfast_diff_norescale
	v_pk_mul_f32 v[80:81], v[80:81], v[178:179] op_sel_hi:[1,0]
	v_pk_mul_f32 v[78:79], v[78:79], v[178:179] op_sel_hi:[1,0]
	v_pk_mul_f32 v[76:77], v[76:77], v[178:179] op_sel_hi:[1,0]
	v_pk_mul_f32 v[74:75], v[74:75], v[178:179] op_sel_hi:[1,0]
	v_pk_mul_f32 v[72:73], v[72:73], v[178:179] op_sel_hi:[1,0]
	v_pk_mul_f32 v[70:71], v[70:71], v[178:179] op_sel_hi:[1,0]
	v_pk_mul_f32 v[68:69], v[68:69], v[178:179] op_sel_hi:[1,0]
	v_pk_mul_f32 v[66:67], v[66:67], v[178:179] op_sel_hi:[1,0]
	v_pk_mul_f32 v[64:65], v[64:65], v[178:179] op_sel_hi:[1,0]
	v_pk_mul_f32 v[62:63], v[62:63], v[178:179] op_sel_hi:[1,0]
	v_pk_mul_f32 v[60:61], v[60:61], v[178:179] op_sel_hi:[1,0]
	v_pk_mul_f32 v[58:59], v[58:59], v[178:179] op_sel_hi:[1,0]
	v_pk_mul_f32 v[56:57], v[56:57], v[178:179] op_sel_hi:[1,0]
	v_pk_mul_f32 v[54:55], v[54:55], v[178:179] op_sel_hi:[1,0]
	v_pk_mul_f32 v[52:53], v[52:53], v[178:179] op_sel_hi:[1,0]
	v_pk_mul_f32 v[50:51], v[50:51], v[178:179] op_sel_hi:[1,0]
	v_pk_mul_f32 v[48:49], v[48:49], v[178:179] op_sel_hi:[1,0]
	v_pk_mul_f32 v[46:47], v[46:47], v[178:179] op_sel_hi:[1,0]
	v_pk_mul_f32 v[44:45], v[44:45], v[178:179] op_sel_hi:[1,0]
	v_pk_mul_f32 v[42:43], v[42:43], v[178:179] op_sel_hi:[1,0]
	v_pk_mul_f32 v[40:41], v[40:41], v[178:179] op_sel_hi:[1,0]
	v_pk_mul_f32 v[38:39], v[38:39], v[178:179] op_sel_hi:[1,0]
	v_pk_mul_f32 v[36:37], v[36:37], v[178:179] op_sel_hi:[1,0]
	v_pk_mul_f32 v[34:35], v[34:35], v[178:179] op_sel_hi:[1,0]
	v_pk_mul_f32 v[32:33], v[32:33], v[178:179] op_sel_hi:[1,0]
	v_pk_mul_f32 v[30:31], v[30:31], v[178:179] op_sel_hi:[1,0]
	v_pk_mul_f32 v[28:29], v[28:29], v[178:179] op_sel_hi:[1,0]
	v_pk_mul_f32 v[26:27], v[26:27], v[178:179] op_sel_hi:[1,0]
	v_pk_mul_f32 v[24:25], v[24:25], v[178:179] op_sel_hi:[1,0]
	v_pk_mul_f32 v[22:23], v[22:23], v[178:179] op_sel_hi:[1,0]
	v_pk_mul_f32 v[20:21], v[20:21], v[178:179] op_sel_hi:[1,0]
	v_pk_mul_f32 v[18:19], v[18:19], v[178:179] op_sel_hi:[1,0]
; template <int MODE, int DK, bool PASS2> ...
;     ...
;                     float ps0 = 0.f, ps1 = 0.f;
; #pragma unroll
;                     for (int r = 0; r < 16; ++r) {
;                         s0[r] = fexp2(__builtin_fmaf(s0[r], sl2, nm)); s1[r] = fexp2(__builtin_fmaf(s1[r], sl2, nm));
;                         ps0 += s0[r]; ps1 += s1[r];
;                     }
;                     l_run = l_run * alpha + (ps0 + ps1);
;                     if (__builtin_amdgcn_ballot_w64(alpha != 1.0f) != 0ull) {
; #pragma unroll
;                         for (int db = 0; db < 4; ++db)
; #pragma unroll
;                             for (int r = 0; r < 16; ++r) O[db][r] *= alpha;
;                     }
;                 } else {
; #pragma unroll
;                     for (int r = 0; r < 16; ++r) { s0[r] *= sl2; s1[r] *= sl2; }
;                     if (need_bias || need_causal || need_win) {
; #pragma unroll
;                         for (int i = 0; i < 32; ++i) {
;                             const int s = kv0 + (i >> 3) * 16 + 8 * g + (i & 7);
;                             const int dist = t_lane - ((MODE == M_CMP) ? 16 * s + 31 : s);
;                             float v = (i < 16) ? s0[i & 15] : s1[i & 15];
;                             if (need_bias) { const int di = dist < 0 ? 0 : (dist > 128 ? 128 : dist); v += tb[di]; }
;                             bool msk = dist < 0;
;                             if (MODE == M_WIN) msk = msk || dist >= 512;
;                             if (msk) v = NEG;
;                             if (i < 16) s0[i & 15] = v; else s1[i & 15] = v;
;                             if ((i & 7) == 7) __builtin_amdgcn_sched_barrier(0);
;                         }
;                     }
;                     if (MODE == M_SLC) {
;                         if (!selbit) {
; #pragma unroll
;                             for (int r = 0; r < 16; ++r) { s0[r] = NEG; s1[r] = NEG; }
;                         }
;                     }
;                     if (!PASS2) {
;                         float mx = fmaxf(s0[0], s1[0]);
; #pragma unroll
;                         for (int r = 1; r < 16; ++r) mx = fmax3(mx, s0[r], s1[r]);
;                         mx = xhalf_max(mx);
;                         const float mn = (mx > m_run + 8.0f) ? mx : m_run;
;                         const float alpha = fexp2(m_run - mn);
;                         m_run = mn;
.Lfast_diff_norescale:
	v_fma_f32 v12, v82, s12, -v207
	v_fma_f32 v13, v83, s12, -v207
	v_exp_f32_e32 v4, v12
	v_exp_f32_e32 v5, v13
	v_fma_f32 v14, v84, s12, -v207
	v_fma_f32 v15, v85, s12, -v207
	v_exp_f32_e32 v6, v14
	v_exp_f32_e32 v7, v15
	v_add_f32_e32 v16, v4, v5
	v_fma_f32 v12, v86, s12, -v207
	v_fma_f32 v13, v87, s12, -v207
	v_exp_f32_e32 v8, v12
	v_exp_f32_e32 v9, v13
	v_cvt_pk_bf16_f32 v236, v4, v5
	v_add_f32_e32 v16, v16, v6
	v_fma_f32 v14, v88, s12, -v207
	v_add_f32_e32 v16, v16, v7
	v_fma_f32 v15, v89, s12, -v207
	v_exp_f32_e32 v10, v14
	v_exp_f32_e32 v11, v15
	v_cvt_pk_bf16_f32 v237, v6, v7
	v_add_f32_e32 v16, v16, v8
	v_add_f32_e32 v16, v16, v9
	v_cvt_pk_bf16_f32 v238, v8, v9
	v_add_f32_e32 v16, v16, v10
	v_add_f32_e32 v16, v16, v11
	v_cvt_pk_bf16_f32 v239, v10, v11
	v_fma_f32 v12, v90, s12, -v207
	v_fma_f32 v13, v91, s12, -v207
	s_waitcnt lgkmcnt(5)
	v_mfma_f32_32x32x16_bf16 v[66:81], v[212:215], v[236:239], v[66:81]
	v_exp_f32_e32 v4, v12
	v_exp_f32_e32 v5, v13
	v_fma_f32 v14, v92, s12, -v207
	v_fma_f32 v15, v93, s12, -v207
	v_exp_f32_e32 v6, v14
	v_exp_f32_e32 v7, v15
	s_waitcnt lgkmcnt(4)
	v_mfma_f32_32x32x16_bf16 v[50:65], v[216:219], v[236:239], v[50:65]
	ds_read_b128 v[212:215], v210 offset:44064
	v_add_f32_e32 v16, v16, v4
	v_fma_f32 v12, v94, s12, -v207
	v_add_f32_e32 v16, v16, v5
	v_fma_f32 v13, v95, s12, -v207
	v_exp_f32_e32 v8, v12
	v_exp_f32_e32 v9, v13
	s_waitcnt lgkmcnt(4)
	v_mfma_f32_32x32x16_bf16 v[34:49], v[220:223], v[236:239], v[34:49]
	ds_read_b128 v[216:219], v210 offset:48672
	v_cvt_pk_bf16_f32 v240, v4, v5
	v_add_f32_e32 v16, v16, v6
	v_fma_f32 v14, v96, s12, -v207
	v_add_f32_e32 v16, v16, v7
	v_fma_f32 v15, v97, s12, -v207
	v_exp_f32_e32 v10, v14
	s_waitcnt lgkmcnt(4)
	v_mfma_f32_32x32x16_bf16 v[18:33], v[224:227], v[236:239], v[18:33]
	ds_read_b128 v[220:223], v210 offset:34880
	v_exp_f32_e32 v11, v15
	v_cvt_pk_bf16_f32 v241, v6, v7
	v_add_f32_e32 v16, v16, v8
	v_add_f32_e32 v16, v16, v9
	v_cvt_pk_bf16_f32 v242, v8, v9
	v_add_f32_e32 v16, v16, v10
	v_add_f32_e32 v16, v16, v11
	v_cvt_pk_bf16_f32 v243, v10, v11
	v_fma_f32 v12, v98, s12, -v207
	v_fma_f32 v13, v99, s12, -v207
	s_waitcnt lgkmcnt(4)
	v_mfma_f32_32x32x16_bf16 v[66:81], v[228:231], v[240:243], v[66:81]
	ds_read_b128 v[224:227], v210 offset:39488
	v_exp_f32_e32 v4, v12
	v_exp_f32_e32 v5, v13
	v_fma_f32 v14, v100, s12, -v207
	v_fma_f32 v15, v101, s12, -v207
	v_exp_f32_e32 v6, v14
	v_exp_f32_e32 v7, v15
	s_waitcnt lgkmcnt(4)
	v_mfma_f32_32x32x16_bf16 v[50:65], v[232:235], v[240:243], v[50:65]
	ds_read_b128 v[228:231], v210 offset:44096
	v_add_f32_e32 v17, v4, v5
	v_fma_f32 v12, v102, s12, -v207
	v_fma_f32 v13, v103, s12, -v207
	v_exp_f32_e32 v8, v12
	v_exp_f32_e32 v9, v13
	v_cvt_pk_bf16_f32 v244, v4, v5
	s_waitcnt lgkmcnt(4)
	v_mfma_f32_32x32x16_bf16 v[34:49], v[212:215], v[240:243], v[34:49]
	ds_read_b128 v[232:235], v210 offset:48704
	v_add_f32_e32 v17, v17, v6
	v_fma_f32 v14, v104, s12, -v207
	v_add_f32_e32 v17, v17, v7
	v_fma_f32 v15, v105, s12, -v207
	v_exp_f32_e32 v10, v14
	v_exp_f32_e32 v11, v15
	s_waitcnt lgkmcnt(4)
	v_mfma_f32_32x32x16_bf16 v[18:33], v[216:219], v[240:243], v[18:33]
	ds_read_b128 v[212:215], v210 offset:34912
	v_cvt_pk_bf16_f32 v245, v6, v7
	v_add_f32_e32 v17, v17, v8
	v_add_f32_e32 v17, v17, v9
	v_cvt_pk_bf16_f32 v246, v8, v9
	v_add_f32_e32 v17, v17, v10
	v_add_f32_e32 v17, v17, v11
	v_cvt_pk_bf16_f32 v247, v10, v11
	v_fma_f32 v12, v106, s12, -v207
	v_fma_f32 v13, v107, s12, -v207
	s_waitcnt lgkmcnt(4)
	v_mfma_f32_32x32x16_bf16 v[66:81], v[220:223], v[244:247], v[66:81]
	ds_read_b128 v[216:219], v210 offset:39520
	v_exp_f32_e32 v4, v12
	v_exp_f32_e32 v5, v13
	v_fma_f32 v14, v108, s12, -v207
	v_fma_f32 v15, v109, s12, -v207
	v_exp_f32_e32 v6, v14
	v_exp_f32_e32 v7, v15
	s_waitcnt lgkmcnt(4)
	v_mfma_f32_32x32x16_bf16 v[50:65], v[224:227], v[244:247], v[50:65]
	ds_read_b128 v[220:223], v210 offset:44128
	v_add_f32_e32 v17, v17, v4
	v_fma_f32 v12, v110, s12, -v207
	v_add_f32_e32 v17, v17, v5
	v_fma_f32 v13, v111, s12, -v207
	v_exp_f32_e32 v8, v12
	v_exp_f32_e32 v9, v13
	s_waitcnt lgkmcnt(4)
	v_mfma_f32_32x32x16_bf16 v[34:49], v[228:231], v[244:247], v[34:49]
	ds_read_b128 v[224:227], v210 offset:48736
	v_cvt_pk_bf16_f32 v248, v4, v5
	v_add_f32_e32 v17, v17, v6
	v_fma_f32 v14, v112, s12, -v207
	v_add_f32_e32 v17, v17, v7
	v_fma_f32 v15, v113, s12, -v207
	v_exp_f32_e32 v10, v14
	s_waitcnt lgkmcnt(4)
	v_mfma_f32_32x32x16_bf16 v[18:33], v[232:235], v[244:247], v[18:33]
	v_exp_f32_e32 v11, v15
	v_cvt_pk_bf16_f32 v249, v6, v7
	v_add_f32_e32 v17, v17, v8
	v_add_f32_e32 v17, v17, v9
	v_cvt_pk_bf16_f32 v250, v8, v9
	v_add_f32_e32 v17, v17, v10
	v_add_f32_e32 v17, v17, v11
	v_cvt_pk_bf16_f32 v251, v10, v11
	v_add_f32_e32 v209, v16, v17
	s_waitcnt lgkmcnt(3)
	v_mfma_f32_32x32x16_bf16 v[66:81], v[212:215], v[248:251], v[66:81]
	v_fmac_f32_e32 v209, v206, v178
	s_waitcnt lgkmcnt(2)
	v_mfma_f32_32x32x16_bf16 v[50:65], v[216:219], v[248:251], v[50:65]
	s_waitcnt lgkmcnt(1)
	v_mfma_f32_32x32x16_bf16 v[34:49], v[220:223], v[248:251], v[34:49]
	s_waitcnt lgkmcnt(0)
	v_mfma_f32_32x32x16_bf16 v[18:33], v[224:227], v[248:251], v[18:33]
	s_setprio 0
	s_branch .Lpostpv_diff

; __device__ __forceinline__ float fexp2(float x) { return __builtin_amdgcn_exp2f(x); }
; __device__ __forceinline__ float fmax3(float a, float b, float c) { float d; asm("v_max3_f32 %0, %1, %2, %3" : "=v"(d) : "v"(a), "v"(b), "v"(c)); return d; }
; template <int MODE, int DK, bool PASS2> ...
;     ...
;                     float mx = fmaxf(s0[0], s1[0]);
; #pragma unroll
;                     for (int r = 1; r < 16; ++r) mx = fmax3(mx, s0[r], s1[r]);
;                     if (MODE == M_SLC) mx = selbit ? mx : NEG;
;                     mx = xhalf_max(mx);
;                     const float mxs = mx * sl2;
;                     const float mn = (mxs > m_run + 8.0f) ? mxs : m_run;
;                     const float alpha = fexp2(m_run - mn);
;                     m_run = mn;
;                     float nm = -mn;
;                     if (MODE == M_SLC) nm = selbit ? nm : -__builtin_inff();
;                     float ps0 = 0.f, ps1 = 0.f;
; #pragma unroll
;                     for (int r = 0; r < 16; ++r) {
;                         s0[r] = fexp2(__builtin_fmaf(s0[r], sl2, nm)); s1[r] = fexp2(__builtin_fmaf(s1[r], sl2, nm));
;                         ps0 += s0[r]; ps1 += s1[r];
;                     }
;                     l_run = l_run * alpha + (ps0 + ps1);
;                     if (__builtin_amdgcn_ballot_w64(alpha != 1.0f) != 0ull) {
; #pragma unroll
;                         for (int db = 0; db < 4; ++db)
; #pragma unroll
;                             for (int r = 0; r < 16; ++r) O[db][r] *= alpha;
;                     }
.Lfast_win:
	s_setprio 1
	s_mul_i32 s98, s89, 0x4800
	v_add_u32_e32 v210, s98, v199
	ds_read_b128 v[212:215], v210 offset:34816
	ds_read_b128 v[216:219], v210 offset:39424
	ds_read_b128 v[220:223], v210 offset:44032
	ds_read_b128 v[224:227], v210 offset:48640
	ds_read_b128 v[228:231], v210 offset:34848
	ds_read_b128 v[232:235], v210 offset:39456
	v_max_f32_e32 v166, v98, v99
	v_max_f32_e32 v167, v82, v83
	v_max3_f32 v166, v166, v100, v101
	v_max3_f32 v167, v167, v84, v85
	v_max3_f32 v166, v166, v102, v103
	v_max3_f32 v167, v167, v86, v87
	v_max3_f32 v166, v166, v104, v105
	v_max3_f32 v167, v167, v88, v89
	v_max3_f32 v166, v166, v106, v107
	v_max3_f32 v167, v167, v90, v91
	v_max3_f32 v166, v166, v108, v109
	v_max3_f32 v167, v167, v92, v93
	v_max3_f32 v166, v166, v110, v111
	v_max3_f32 v167, v167, v94, v95
	v_max3_f32 v166, v166, v112, v113
	v_max3_f32 v167, v167, v96, v97
	v_max_f32_e32 v166, v166, v167
	v_mov_b32_e32 v167, v166
	s_nop 1
	v_permlane32_swap_b32_e32 v166, v167
	v_max_f32_e32 v166, v166, v167
	v_mul_f32_e32 v166, 0x3e0293ee, v166
	v_cmp_gt_f32_e32 vcc, v166, v2
	s_nop 1
	v_cndmask_b32_e32 v208, v207, v166, vcc
	v_sub_f32_e32 v167, v207, v208
	v_exp_f32_e32 v2, v167
	s_nop 0
	v_cmp_neq_f32_e32 vcc, 1.0, v2
	s_cbranch_vccz .Lfast_win_norescale
	v_pk_mul_f32 v[80:81], v[80:81], v[2:3] op_sel_hi:[1,0]
	v_pk_mul_f32 v[78:79], v[78:79], v[2:3] op_sel_hi:[1,0]
	v_pk_mul_f32 v[76:77], v[76:77], v[2:3] op_sel_hi:[1,0]
	v_pk_mul_f32 v[74:75], v[74:75], v[2:3] op_sel_hi:[1,0]
	v_pk_mul_f32 v[72:73], v[72:73], v[2:3] op_sel_hi:[1,0]
	v_pk_mul_f32 v[70:71], v[70:71], v[2:3] op_sel_hi:[1,0]
	v_pk_mul_f32 v[68:69], v[68:69], v[2:3] op_sel_hi:[1,0]
	v_pk_mul_f32 v[66:67], v[66:67], v[2:3] op_sel_hi:[1,0]
	v_pk_mul_f32 v[64:65], v[64:65], v[2:3] op_sel_hi:[1,0]
	v_pk_mul_f32 v[62:63], v[62:63], v[2:3] op_sel_hi:[1,0]
	v_pk_mul_f32 v[60:61], v[60:61], v[2:3] op_sel_hi:[1,0]
	v_pk_mul_f32 v[58:59], v[58:59], v[2:3] op_sel_hi:[1,0]
	v_pk_mul_f32 v[56:57], v[56:57], v[2:3] op_sel_hi:[1,0]
	v_pk_mul_f32 v[54:55], v[54:55], v[2:3] op_sel_hi:[1,0]
	v_pk_mul_f32 v[52:53], v[52:53], v[2:3] op_sel_hi:[1,0]
	v_pk_mul_f32 v[50:51], v[50:51], v[2:3] op_sel_hi:[1,0]
	v_pk_mul_f32 v[48:49], v[48:49], v[2:3] op_sel_hi:[1,0]
	v_pk_mul_f32 v[46:47], v[46:47], v[2:3] op_sel_hi:[1,0]
	v_pk_mul_f32 v[44:45], v[44:45], v[2:3] op_sel_hi:[1,0]
	v_pk_mul_f32 v[42:43], v[42:43], v[2:3] op_sel_hi:[1,0]
	v_pk_mul_f32 v[40:41], v[40:41], v[2:3] op_sel_hi:[1,0]
	v_pk_mul_f32 v[38:39], v[38:39], v[2:3] op_sel_hi:[1,0]
	v_pk_mul_f32 v[36:37], v[36:37], v[2:3] op_sel_hi:[1,0]
	v_pk_mul_f32 v[34:35], v[34:35], v[2:3] op_sel_hi:[1,0]
	v_pk_mul_f32 v[32:33], v[32:33], v[2:3] op_sel_hi:[1,0]
	v_pk_mul_f32 v[30:31], v[30:31], v[2:3] op_sel_hi:[1,0]
	v_pk_mul_f32 v[28:29], v[28:29], v[2:3] op_sel_hi:[1,0]
	v_pk_mul_f32 v[26:27], v[26:27], v[2:3] op_sel_hi:[1,0]
	v_pk_mul_f32 v[24:25], v[24:25], v[2:3] op_sel_hi:[1,0]
	v_pk_mul_f32 v[22:23], v[22:23], v[2:3] op_sel_hi:[1,0]
	v_pk_mul_f32 v[20:21], v[20:21], v[2:3] op_sel_hi:[1,0]
	v_pk_mul_f32 v[18:19], v[18:19], v[2:3] op_sel_hi:[1,0]
; template <int MODE, int DK, bool PASS2> ...
;     ...
;                     float ps0 = 0.f, ps1 = 0.f;
; #pragma unroll
;                     for (int r = 0; r < 16; ++r) {
;                         s0[r] = fexp2(__builtin_fmaf(s0[r], sl2, nm)); s1[r] = fexp2(__builtin_fmaf(s1[r], sl2, nm));
;                         ps0 += s0[r]; ps1 += s1[r];
;                     }
;                     l_run = l_run * alpha + (ps0 + ps1);
;                     if (__builtin_amdgcn_ballot_w64(alpha != 1.0f) != 0ull) {
; #pragma unroll
;                         for (int db = 0; db < 4; ++db)
; #pragma unroll
;                             for (int r = 0; r < 16; ++r) O[db][r] *= alpha;
;                     }
;                 } else {
; #pragma unroll
;                     for (int r = 0; r < 16; ++r) { s0[r] *= sl2; s1[r] *= sl2; }
;                     if (need_bias || need_causal || need_win) {
; #pragma unroll
;                         for (int i = 0; i < 32; ++i) {
;                             const int s = kv0 + (i >> 3) * 16 + 8 * g + (i & 7);
;                             const int dist = t_lane - ((MODE == M_CMP) ? 16 * s + 31 : s);
;                             float v = (i < 16) ? s0[i & 15] : s1[i & 15];
;                             if (need_bias) { const int di = dist < 0 ? 0 : (dist > 128 ? 128 : dist); v += tb[di]; }
;                             bool msk = dist < 0;
;                             if (MODE == M_WIN) msk = msk || dist >= 512;
;                             if (msk) v = NEG;
;                             if (i < 16) s0[i & 15] = v; else s1[i & 15] = v;
;                             if ((i & 7) == 7) __builtin_amdgcn_sched_barrier(0);
;                         }
;                     }
;                     if (MODE == M_SLC) {
;                         if (!selbit) {
; #pragma unroll
;                             for (int r = 0; r < 16; ++r) { s0[r] = NEG; s1[r] = NEG; }
;                         }
;                     }
;                     if (!PASS2) {
;                         float mx = fmaxf(s0[0], s1[0]);
; #pragma unroll
;                         for (int r = 1; r < 16; ++r) mx = fmax3(mx, s0[r], s1[r]);
;                         mx = xhalf_max(mx);
;                         const float mn = (mx > m_run + 8.0f) ? mx : m_run;
;                         const float alpha = fexp2(m_run - mn);
;                         m_run = mn;
.Lfast_win_norescale:
	v_fma_f32 v12, v98, s58, -v208
	v_fma_f32 v13, v99, s58, -v208
	v_exp_f32_e32 v4, v12
	v_exp_f32_e32 v5, v13
	v_fma_f32 v14, v100, s58, -v208
	v_fma_f32 v15, v101, s58, -v208
	v_exp_f32_e32 v6, v14
	v_exp_f32_e32 v7, v15
	v_add_f32_e32 v16, v4, v5
	v_fma_f32 v12, v102, s58, -v208
	v_fma_f32 v13, v103, s58, -v208
	v_exp_f32_e32 v8, v12
	v_exp_f32_e32 v9, v13
	v_cvt_pk_bf16_f32 v236, v4, v5
	v_add_f32_e32 v16, v16, v6
	v_fma_f32 v14, v104, s58, -v208
	v_add_f32_e32 v16, v16, v7
	v_fma_f32 v15, v105, s58, -v208
	v_exp_f32_e32 v10, v14
	v_exp_f32_e32 v11, v15
	v_cvt_pk_bf16_f32 v237, v6, v7
	v_add_f32_e32 v16, v16, v8
	v_add_f32_e32 v16, v16, v9
	v_cvt_pk_bf16_f32 v238, v8, v9
	v_add_f32_e32 v16, v16, v10
	v_add_f32_e32 v16, v16, v11
	v_cvt_pk_bf16_f32 v239, v10, v11
	v_fma_f32 v12, v106, s58, -v208
	v_fma_f32 v13, v107, s58, -v208
	s_waitcnt lgkmcnt(5)
	v_mfma_f32_32x32x16_bf16 v[66:81], v[212:215], v[236:239], v[66:81]
	v_exp_f32_e32 v4, v12
	v_exp_f32_e32 v5, v13
	v_fma_f32 v14, v108, s58, -v208
	v_fma_f32 v15, v109, s58, -v208
	v_exp_f32_e32 v6, v14
	v_exp_f32_e32 v7, v15
	s_waitcnt lgkmcnt(4)
	v_mfma_f32_32x32x16_bf16 v[50:65], v[216:219], v[236:239], v[50:65]
	ds_read_b128 v[212:215], v210 offset:44064
	v_add_f32_e32 v16, v16, v4
	v_fma_f32 v12, v110, s58, -v208
	v_add_f32_e32 v16, v16, v5
	v_fma_f32 v13, v111, s58, -v208
	v_exp_f32_e32 v8, v12
	v_exp_f32_e32 v9, v13
	s_waitcnt lgkmcnt(4)
	v_mfma_f32_32x32x16_bf16 v[34:49], v[220:223], v[236:239], v[34:49]
	ds_read_b128 v[216:219], v210 offset:48672
	v_cvt_pk_bf16_f32 v240, v4, v5
	v_add_f32_e32 v16, v16, v6
	v_fma_f32 v14, v112, s58, -v208
	v_add_f32_e32 v16, v16, v7
	v_fma_f32 v15, v113, s58, -v208
	v_exp_f32_e32 v10, v14
	s_waitcnt lgkmcnt(4)
	v_mfma_f32_32x32x16_bf16 v[18:33], v[224:227], v[236:239], v[18:33]
	ds_read_b128 v[220:223], v210 offset:34880
	v_exp_f32_e32 v11, v15
	v_cvt_pk_bf16_f32 v241, v6, v7
	v_add_f32_e32 v16, v16, v8
	v_add_f32_e32 v16, v16, v9
	v_cvt_pk_bf16_f32 v242, v8, v9
	v_add_f32_e32 v16, v16, v10
	v_add_f32_e32 v16, v16, v11
	v_cvt_pk_bf16_f32 v243, v10, v11
	v_fma_f32 v12, v82, s58, -v208
	v_fma_f32 v13, v83, s58, -v208
	s_waitcnt lgkmcnt(4)
	v_mfma_f32_32x32x16_bf16 v[66:81], v[228:231], v[240:243], v[66:81]
	ds_read_b128 v[224:227], v210 offset:39488
	v_exp_f32_e32 v4, v12
	v_exp_f32_e32 v5, v13
	v_fma_f32 v14, v84, s58, -v208
	v_fma_f32 v15, v85, s58, -v208
	v_exp_f32_e32 v6, v14
	v_exp_f32_e32 v7, v15
	s_waitcnt lgkmcnt(4)
	v_mfma_f32_32x32x16_bf16 v[50:65], v[232:235], v[240:243], v[50:65]
	ds_read_b128 v[228:231], v210 offset:44096
	v_add_f32_e32 v17, v4, v5
	v_fma_f32 v12, v86, s58, -v208
	v_fma_f32 v13, v87, s58, -v208
	v_exp_f32_e32 v8, v12
	v_exp_f32_e32 v9, v13
	v_cvt_pk_bf16_f32 v244, v4, v5
	s_waitcnt lgkmcnt(4)
	v_mfma_f32_32x32x16_bf16 v[34:49], v[212:215], v[240:243], v[34:49]
	ds_read_b128 v[232:235], v210 offset:48704
	v_add_f32_e32 v17, v17, v6
	v_fma_f32 v14, v88, s58, -v208
	v_add_f32_e32 v17, v17, v7
	v_fma_f32 v15, v89, s58, -v208
	v_exp_f32_e32 v10, v14
	v_exp_f32_e32 v11, v15
	s_waitcnt lgkmcnt(4)
	v_mfma_f32_32x32x16_bf16 v[18:33], v[216:219], v[240:243], v[18:33]
	ds_read_b128 v[212:215], v210 offset:34912
	v_cvt_pk_bf16_f32 v245, v6, v7
	v_add_f32_e32 v17, v17, v8
	v_add_f32_e32 v17, v17, v9
	v_cvt_pk_bf16_f32 v246, v8, v9
	v_add_f32_e32 v17, v17, v10
	v_add_f32_e32 v17, v17, v11
	v_cvt_pk_bf16_f32 v247, v10, v11
	v_fma_f32 v12, v90, s58, -v208
	v_fma_f32 v13, v91, s58, -v208
	s_waitcnt lgkmcnt(4)
	v_mfma_f32_32x32x16_bf16 v[66:81], v[220:223], v[244:247], v[66:81]
	ds_read_b128 v[216:219], v210 offset:39520
	v_exp_f32_e32 v4, v12
	v_exp_f32_e32 v5, v13
	v_fma_f32 v14, v92, s58, -v208
	v_fma_f32 v15, v93, s58, -v208
	v_exp_f32_e32 v6, v14
	v_exp_f32_e32 v7, v15
	s_waitcnt lgkmcnt(4)
	v_mfma_f32_32x32x16_bf16 v[50:65], v[224:227], v[244:247], v[50:65]
	ds_read_b128 v[220:223], v210 offset:44128
	v_add_f32_e32 v17, v17, v4
	v_fma_f32 v12, v94, s58, -v208
	v_add_f32_e32 v17, v17, v5
	v_fma_f32 v13, v95, s58, -v208
	v_exp_f32_e32 v8, v12
	v_exp_f32_e32 v9, v13
	s_waitcnt lgkmcnt(4)
	v_mfma_f32_32x32x16_bf16 v[34:49], v[228:231], v[244:247], v[34:49]
	ds_read_b128 v[224:227], v210 offset:48736
	v_cvt_pk_bf16_f32 v248, v4, v5
	v_add_f32_e32 v17, v17, v6
	v_fma_f32 v14, v96, s58, -v208
	v_add_f32_e32 v17, v17, v7
	v_fma_f32 v15, v97, s58, -v208
	v_exp_f32_e32 v10, v14
	s_waitcnt lgkmcnt(4)
	v_mfma_f32_32x32x16_bf16 v[18:33], v[232:235], v[244:247], v[18:33]
	v_exp_f32_e32 v11, v15
	v_cvt_pk_bf16_f32 v249, v6, v7
	v_add_f32_e32 v17, v17, v8
	v_add_f32_e32 v17, v17, v9
	v_cvt_pk_bf16_f32 v250, v8, v9
	v_add_f32_e32 v17, v17, v10
	v_add_f32_e32 v17, v17, v11
	v_cvt_pk_bf16_f32 v251, v10, v11
	v_add_f32_e32 v209, v16, v17
	s_waitcnt lgkmcnt(3)
	v_mfma_f32_32x32x16_bf16 v[66:81], v[212:215], v[248:251], v[66:81]
	v_fmac_f32_e32 v209, v206, v2
	s_waitcnt lgkmcnt(2)
	v_mfma_f32_32x32x16_bf16 v[50:65], v[216:219], v[248:251], v[50:65]
	s_waitcnt lgkmcnt(1)
	v_mfma_f32_32x32x16_bf16 v[34:49], v[220:223], v[248:251], v[34:49]
	s_waitcnt lgkmcnt(0)
	v_mfma_f32_32x32x16_bf16 v[18:33], v[224:227], v[248:251], v[18:33]
	s_setprio 0
	s_branch .Lpostpv_win

; __device__ __forceinline__ float fexp2(float x) { return __builtin_amdgcn_exp2f(x); }
; __device__ __forceinline__ float fmax3(float a, float b, float c) { float d; asm("v_max3_f32 %0, %1, %2, %3" : "=v"(d) : "v"(a), "v"(b), "v"(c)); return d; }
; template <int MODE, int DK, bool PASS2> ...
;     ...
;                     float mx = fmaxf(s0[0], s1[0]);
; #pragma unroll
;                     for (int r = 1; r < 16; ++r) mx = fmax3(mx, s0[r], s1[r]);
;                     if (MODE == M_SLC) mx = selbit ? mx : NEG;
;                     mx = xhalf_max(mx);
;                     const float mxs = mx * sl2;
;                     const float mn = (mxs > m_run + 8.0f) ? mxs : m_run;
;                     const float alpha = fexp2(m_run - mn);
;                     m_run = mn;
;                     float nm = -mn;
;                     if (MODE == M_SLC) nm = selbit ? nm : -__builtin_inff();
;                     float ps0 = 0.f, ps1 = 0.f;
; #pragma unroll
;                     for (int r = 0; r < 16; ++r) {
;                         s0[r] = fexp2(__builtin_fmaf(s0[r], sl2, nm)); s1[r] = fexp2(__builtin_fmaf(s1[r], sl2, nm));
;                         ps0 += s0[r]; ps1 += s1[r];
;                     }
;                     l_run = l_run * alpha + (ps0 + ps1);
;                     if (__builtin_amdgcn_ballot_w64(alpha != 1.0f) != 0ull) {
; #pragma unroll
;                         for (int db = 0; db < 4; ++db)
; #pragma unroll
;                             for (int r = 0; r < 16; ++r) O[db][r] *= alpha;
;                     }
.Lfast_cmp1:
	s_setprio 1
	s_mul_i32 s98, s39, 0x4800
	v_add_u32_e32 v216, s98, v240
	ds_read_b128 v[204:207], v216 offset:34816
	ds_read_b128 v[208:211], v216 offset:39424
	ds_read_b128 v[212:215], v216 offset:44032
	v_max_f32_e32 v200, v82, v83
	v_max_f32_e32 v201, v98, v99
	v_max3_f32 v200, v200, v84, v85
	v_max3_f32 v201, v201, v100, v101
	v_max3_f32 v200, v200, v86, v87
	v_max3_f32 v201, v201, v102, v103
	v_max3_f32 v200, v200, v88, v89
	v_max3_f32 v201, v201, v104, v105
	v_max3_f32 v200, v200, v90, v91
	v_max3_f32 v201, v201, v106, v107
	v_max3_f32 v200, v200, v92, v93
	v_max3_f32 v201, v201, v108, v109
	v_max3_f32 v200, v200, v94, v95
	v_max3_f32 v201, v201, v110, v111
	v_max3_f32 v200, v200, v96, v97
	v_max3_f32 v201, v201, v112, v113
	v_max_f32_e32 v200, v200, v201
	v_mov_b32_e32 v201, v200
	s_nop 1
	v_permlane32_swap_b32_e32 v200, v201
	v_max_f32_e32 v200, v200, v201
	v_mul_f32_e32 v200, 0x3e0293ee, v200
	v_cmp_gt_f32_e32 vcc, v200, v2
	s_nop 1
	v_cndmask_b32_e32 v250, v249, v200, vcc
	v_sub_f32_e32 v201, v249, v250
	v_exp_f32_e32 v2, v201
	s_nop 0
	v_cmp_neq_f32_e32 vcc, 1.0, v2
	s_cbranch_vccz .Lfast_cmp1_norescale
	v_pk_mul_f32 v[80:81], v[80:81], v[2:3] op_sel_hi:[1,0]
	v_pk_mul_f32 v[78:79], v[78:79], v[2:3] op_sel_hi:[1,0]
	v_pk_mul_f32 v[76:77], v[76:77], v[2:3] op_sel_hi:[1,0]
	v_pk_mul_f32 v[74:75], v[74:75], v[2:3] op_sel_hi:[1,0]
	v_pk_mul_f32 v[72:73], v[72:73], v[2:3] op_sel_hi:[1,0]
	v_pk_mul_f32 v[70:71], v[70:71], v[2:3] op_sel_hi:[1,0]
	v_pk_mul_f32 v[68:69], v[68:69], v[2:3] op_sel_hi:[1,0]
	v_pk_mul_f32 v[66:67], v[66:67], v[2:3] op_sel_hi:[1,0]
	v_pk_mul_f32 v[64:65], v[64:65], v[2:3] op_sel_hi:[1,0]
	v_pk_mul_f32 v[62:63], v[62:63], v[2:3] op_sel_hi:[1,0]
	v_pk_mul_f32 v[60:61], v[60:61], v[2:3] op_sel_hi:[1,0]
	v_pk_mul_f32 v[58:59], v[58:59], v[2:3] op_sel_hi:[1,0]
	v_pk_mul_f32 v[56:57], v[56:57], v[2:3] op_sel_hi:[1,0]
	v_pk_mul_f32 v[54:55], v[54:55], v[2:3] op_sel_hi:[1,0]
	v_pk_mul_f32 v[52:53], v[52:53], v[2:3] op_sel_hi:[1,0]
	v_pk_mul_f32 v[50:51], v[50:51], v[2:3] op_sel_hi:[1,0]
	v_pk_mul_f32 v[48:49], v[48:49], v[2:3] op_sel_hi:[1,0]
	v_pk_mul_f32 v[46:47], v[46:47], v[2:3] op_sel_hi:[1,0]
	v_pk_mul_f32 v[44:45], v[44:45], v[2:3] op_sel_hi:[1,0]
	v_pk_mul_f32 v[42:43], v[42:43], v[2:3] op_sel_hi:[1,0]
	v_pk_mul_f32 v[40:41], v[40:41], v[2:3] op_sel_hi:[1,0]
	v_pk_mul_f32 v[38:39], v[38:39], v[2:3] op_sel_hi:[1,0]
	v_pk_mul_f32 v[36:37], v[36:37], v[2:3] op_sel_hi:[1,0]
	v_pk_mul_f32 v[34:35], v[34:35], v[2:3] op_sel_hi:[1,0]
	v_pk_mul_f32 v[32:33], v[32:33], v[2:3] op_sel_hi:[1,0]
	v_pk_mul_f32 v[30:31], v[30:31], v[2:3] op_sel_hi:[1,0]
	v_pk_mul_f32 v[28:29], v[28:29], v[2:3] op_sel_hi:[1,0]
	v_pk_mul_f32 v[26:27], v[26:27], v[2:3] op_sel_hi:[1,0]
	v_pk_mul_f32 v[24:25], v[24:25], v[2:3] op_sel_hi:[1,0]
	v_pk_mul_f32 v[22:23], v[22:23], v[2:3] op_sel_hi:[1,0]
	v_pk_mul_f32 v[20:21], v[20:21], v[2:3] op_sel_hi:[1,0]
	v_pk_mul_f32 v[18:19], v[18:19], v[2:3] op_sel_hi:[1,0]
; template <int MODE, int DK, bool PASS2> ...
;     ...
;                     float ps0 = 0.f, ps1 = 0.f;
; #pragma unroll
;                     for (int r = 0; r < 16; ++r) {
;                         s0[r] = fexp2(__builtin_fmaf(s0[r], sl2, nm)); s1[r] = fexp2(__builtin_fmaf(s1[r], sl2, nm));
;                         ps0 += s0[r]; ps1 += s1[r];
;                     }
;                     l_run = l_run * alpha + (ps0 + ps1);
;                     if (__builtin_amdgcn_ballot_w64(alpha != 1.0f) != 0ull) {
; #pragma unroll
;                         for (int db = 0; db < 4; ++db)
; #pragma unroll
;                             for (int r = 0; r < 16; ++r) O[db][r] *= alpha;
;                     }
;                 } else {
; #pragma unroll
;                     for (int r = 0; r < 16; ++r) { s0[r] *= sl2; s1[r] *= sl2; }
;                     if (need_bias || need_causal || need_win) {
; #pragma unroll
;                         for (int i = 0; i < 32; ++i) {
;                             const int s = kv0 + (i >> 3) * 16 + 8 * g + (i & 7);
;                             const int dist = t_lane - ((MODE == M_CMP) ? 16 * s + 31 : s);
;                             float v = (i < 16) ? s0[i & 15] : s1[i & 15];
;                             if (need_bias) { const int di = dist < 0 ? 0 : (dist > 128 ? 128 : dist); v += tb[di]; }
;                             bool msk = dist < 0;
;                             if (MODE == M_WIN) msk = msk || dist >= 512;
;                             if (msk) v = NEG;
;                             if (i < 16) s0[i & 15] = v; else s1[i & 15] = v;
;                             if ((i & 7) == 7) __builtin_amdgcn_sched_barrier(0);
;                         }
;                     }
;                     if (MODE == M_SLC) {
;                         if (!selbit) {
; #pragma unroll
;                             for (int r = 0; r < 16; ++r) { s0[r] = NEG; s1[r] = NEG; }
;                         }
;                     }
;                     if (!PASS2) {
;                         float mx = fmaxf(s0[0], s1[0]);
; #pragma unroll
;                         for (int r = 1; r < 16; ++r) mx = fmax3(mx, s0[r], s1[r]);
;                         mx = xhalf_max(mx);
;                         const float mn = (mx > m_run + 8.0f) ? mx : m_run;
;                         const float alpha = fexp2(m_run - mn);
;                         m_run = mn;
.Lfast_cmp1_norescale:
	v_fma_f32 v12, v82, s34, -v250
	v_fma_f32 v13, v83, s34, -v250
	v_exp_f32_e32 v4, v12
	v_exp_f32_e32 v5, v13
	v_fma_f32 v14, v84, s34, -v250
	v_fma_f32 v15, v85, s34, -v250
	v_exp_f32_e32 v6, v14
	v_exp_f32_e32 v7, v15
	v_add_f32_e32 v16, v4, v5
	v_fma_f32 v12, v86, s34, -v250
	v_fma_f32 v13, v87, s34, -v250
	v_exp_f32_e32 v8, v12
	v_exp_f32_e32 v9, v13
	v_cvt_pk_bf16_f32 v82, v4, v5
	v_add_f32_e32 v16, v16, v6
	v_fma_f32 v14, v88, s34, -v250
	v_add_f32_e32 v16, v16, v7
	v_fma_f32 v15, v89, s34, -v250
	v_exp_f32_e32 v10, v14
	v_exp_f32_e32 v11, v15
	v_cvt_pk_bf16_f32 v83, v6, v7
	v_add_f32_e32 v16, v16, v8
	v_add_f32_e32 v16, v16, v9
	v_cvt_pk_bf16_f32 v84, v8, v9
	v_add_f32_e32 v16, v16, v10
	v_add_f32_e32 v16, v16, v11
	v_cvt_pk_bf16_f32 v85, v10, v11
	v_fma_f32 v12, v90, s34, -v250
	v_fma_f32 v13, v91, s34, -v250
	s_waitcnt lgkmcnt(2)
	v_mfma_f32_32x32x16_bf16 v[66:81], v[204:207], v[82:85], v[66:81]
	v_exp_f32_e32 v4, v12
	v_exp_f32_e32 v5, v13
	v_fma_f32 v14, v92, s34, -v250
	v_fma_f32 v15, v93, s34, -v250
	v_exp_f32_e32 v6, v14
	v_exp_f32_e32 v7, v15
	s_waitcnt lgkmcnt(1)
	v_mfma_f32_32x32x16_bf16 v[50:65], v[208:211], v[82:85], v[50:65]
	ds_read_b128 v[204:207], v216 offset:48640
	v_add_f32_e32 v16, v16, v4
	v_fma_f32 v12, v94, s34, -v250
	v_add_f32_e32 v16, v16, v5
	v_fma_f32 v13, v95, s34, -v250
	v_exp_f32_e32 v8, v12
	v_exp_f32_e32 v9, v13
	s_waitcnt lgkmcnt(1)
	v_mfma_f32_32x32x16_bf16 v[34:49], v[212:215], v[82:85], v[34:49]
	ds_read_b128 v[208:211], v216 offset:34848
	v_cvt_pk_bf16_f32 v90, v4, v5
	v_add_f32_e32 v16, v16, v6
	v_fma_f32 v14, v96, s34, -v250
	v_add_f32_e32 v16, v16, v7
	v_fma_f32 v15, v97, s34, -v250
	v_exp_f32_e32 v10, v14
	s_waitcnt lgkmcnt(1)
	v_mfma_f32_32x32x16_bf16 v[18:33], v[204:207], v[82:85], v[18:33]
	ds_read_b128 v[212:215], v216 offset:39456
	v_exp_f32_e32 v11, v15
	v_cvt_pk_bf16_f32 v91, v6, v7
	v_add_f32_e32 v16, v16, v8
	v_add_f32_e32 v16, v16, v9
	v_cvt_pk_bf16_f32 v92, v8, v9
	v_add_f32_e32 v16, v16, v10
	v_add_f32_e32 v16, v16, v11
	v_cvt_pk_bf16_f32 v93, v10, v11
	v_fma_f32 v12, v98, s34, -v250
	v_fma_f32 v13, v99, s34, -v250
	s_waitcnt lgkmcnt(1)
	v_mfma_f32_32x32x16_bf16 v[66:81], v[208:211], v[90:93], v[66:81]
	ds_read_b128 v[204:207], v216 offset:44064
	v_exp_f32_e32 v4, v12
	v_exp_f32_e32 v5, v13
	v_fma_f32 v14, v100, s34, -v250
	v_fma_f32 v15, v101, s34, -v250
	v_exp_f32_e32 v6, v14
	v_exp_f32_e32 v7, v15
	s_waitcnt lgkmcnt(1)
	v_mfma_f32_32x32x16_bf16 v[50:65], v[212:215], v[90:93], v[50:65]
	ds_read_b128 v[208:211], v216 offset:48672
	v_add_f32_e32 v17, v4, v5
	v_fma_f32 v12, v102, s34, -v250
	v_fma_f32 v13, v103, s34, -v250
	v_exp_f32_e32 v8, v12
	v_exp_f32_e32 v9, v13
	v_cvt_pk_bf16_f32 v98, v4, v5
	s_waitcnt lgkmcnt(1)
	v_mfma_f32_32x32x16_bf16 v[34:49], v[204:207], v[90:93], v[34:49]
	ds_read_b128 v[212:215], v216 offset:34880
	v_add_f32_e32 v17, v17, v6
	v_fma_f32 v14, v104, s34, -v250
	v_add_f32_e32 v17, v17, v7
	v_fma_f32 v15, v105, s34, -v250
	v_exp_f32_e32 v10, v14
	v_exp_f32_e32 v11, v15
	s_waitcnt lgkmcnt(1)
	v_mfma_f32_32x32x16_bf16 v[18:33], v[208:211], v[90:93], v[18:33]
	ds_read_b128 v[204:207], v216 offset:39488
	v_cvt_pk_bf16_f32 v99, v6, v7
	v_add_f32_e32 v17, v17, v8
	v_add_f32_e32 v17, v17, v9
	v_cvt_pk_bf16_f32 v100, v8, v9
	v_add_f32_e32 v17, v17, v10
	v_add_f32_e32 v17, v17, v11
	v_cvt_pk_bf16_f32 v101, v10, v11
	v_fma_f32 v12, v106, s34, -v250
	v_fma_f32 v13, v107, s34, -v250
	s_waitcnt lgkmcnt(1)
	v_mfma_f32_32x32x16_bf16 v[66:81], v[212:215], v[98:101], v[66:81]
	ds_read_b128 v[208:211], v216 offset:44096
	v_exp_f32_e32 v4, v12
	v_exp_f32_e32 v5, v13
	v_fma_f32 v14, v108, s34, -v250
	v_fma_f32 v15, v109, s34, -v250
	v_exp_f32_e32 v6, v14
	v_exp_f32_e32 v7, v15
	s_waitcnt lgkmcnt(1)
	v_mfma_f32_32x32x16_bf16 v[50:65], v[204:207], v[98:101], v[50:65]
	ds_read_b128 v[212:215], v216 offset:48704
	v_add_f32_e32 v17, v17, v4
	v_fma_f32 v12, v110, s34, -v250
	v_add_f32_e32 v17, v17, v5
	v_fma_f32 v13, v111, s34, -v250
	v_exp_f32_e32 v8, v12
	v_exp_f32_e32 v9, v13
	s_waitcnt lgkmcnt(1)
	v_mfma_f32_32x32x16_bf16 v[34:49], v[208:211], v[98:101], v[34:49]
	ds_read_b128 v[204:207], v216 offset:34912
	v_cvt_pk_bf16_f32 v106, v4, v5
	v_add_f32_e32 v17, v17, v6
	v_fma_f32 v14, v112, s34, -v250
	v_add_f32_e32 v17, v17, v7
	v_fma_f32 v15, v113, s34, -v250
	v_exp_f32_e32 v10, v14
	s_waitcnt lgkmcnt(1)
	v_mfma_f32_32x32x16_bf16 v[18:33], v[212:215], v[98:101], v[18:33]
	ds_read_b128 v[208:211], v216 offset:39520
	v_exp_f32_e32 v11, v15
	v_cvt_pk_bf16_f32 v107, v6, v7
	v_add_f32_e32 v17, v17, v8
	v_add_f32_e32 v17, v17, v9
	v_cvt_pk_bf16_f32 v108, v8, v9
	v_add_f32_e32 v17, v17, v10
	v_add_f32_e32 v17, v17, v11
	v_cvt_pk_bf16_f32 v109, v10, v11
	v_add_f32_e32 v251, v16, v17
	s_waitcnt lgkmcnt(1)
	v_mfma_f32_32x32x16_bf16 v[66:81], v[204:207], v[106:109], v[66:81]
	ds_read_b128 v[212:215], v216 offset:44128
	v_fmac_f32_e32 v251, v248, v2
	s_waitcnt lgkmcnt(1)
	v_mfma_f32_32x32x16_bf16 v[50:65], v[208:211], v[106:109], v[50:65]
	ds_read_b128 v[204:207], v216 offset:48736
	s_waitcnt lgkmcnt(1)
	v_mfma_f32_32x32x16_bf16 v[34:49], v[212:215], v[106:109], v[34:49]
	s_waitcnt lgkmcnt(0)
	v_mfma_f32_32x32x16_bf16 v[18:33], v[204:207], v[106:109], v[18:33]
	s_setprio 0
	s_branch .Lpostpv_cmp1

; __device__ __forceinline__ float fexp2(float x) { return __builtin_amdgcn_exp2f(x); }
; __device__ __forceinline__ float fmax3(float a, float b, float c) { float d; asm("v_max3_f32 %0, %1, %2, %3" : "=v"(d) : "v"(a), "v"(b), "v"(c)); return d; }
; template <int MODE, int DK, bool PASS2> ...
;     ...
;                     float mx = fmaxf(s0[0], s1[0]);
; #pragma unroll
;                     for (int r = 1; r < 16; ++r) mx = fmax3(mx, s0[r], s1[r]);
;                     if (MODE == M_SLC) mx = selbit ? mx : NEG;
;                     mx = xhalf_max(mx);
;                     const float mxs = mx * sl2;
;                     const float mn = (mxs > m_run + 8.0f) ? mxs : m_run;
;                     const float alpha = fexp2(m_run - mn);
;                     m_run = mn;
;                     float nm = -mn;
;                     if (MODE == M_SLC) nm = selbit ? nm : -__builtin_inff();
;                     float ps0 = 0.f, ps1 = 0.f;
; #pragma unroll
;                     for (int r = 0; r < 16; ++r) {
;                         s0[r] = fexp2(__builtin_fmaf(s0[r], sl2, nm)); s1[r] = fexp2(__builtin_fmaf(s1[r], sl2, nm));
;                         ps0 += s0[r]; ps1 += s1[r];
;                     }
;                     l_run = l_run * alpha + (ps0 + ps1);
;                     if (__builtin_amdgcn_ballot_w64(alpha != 1.0f) != 0ull) {
; #pragma unroll
;                         for (int db = 0; db < 4; ++db)
; #pragma unroll
;                             for (int r = 0; r < 16; ++r) O[db][r] *= alpha;
;                     }
.Lfast_slc:
	s_setprio 1
	s_mul_i32 s98, s74, 0x4800
	v_add_u32_e32 v220, s98, v214
	ds_read_b128 v[222:225], v220 offset:34816
	ds_read_b128 v[226:229], v220 offset:39424
	ds_read_b128 v[230:233], v220 offset:44032
	ds_read_b128 v[234:237], v220 offset:48640
	ds_read_b128 v[238:241], v220 offset:34848
	ds_read_b128 v[242:245], v220 offset:39456
	v_max_f32_e32 v174, v98, v99
	v_max_f32_e32 v175, v82, v83
	v_max3_f32 v174, v174, v100, v101
	v_max3_f32 v175, v175, v84, v85
	v_max3_f32 v174, v174, v102, v103
	v_max3_f32 v175, v175, v86, v87
	v_max3_f32 v174, v174, v104, v105
	v_max3_f32 v175, v175, v88, v89
	v_max3_f32 v174, v174, v106, v107
	v_max3_f32 v175, v175, v90, v91
	v_max3_f32 v174, v174, v108, v109
	v_max3_f32 v175, v175, v92, v93
	v_max3_f32 v174, v174, v110, v111
	v_max3_f32 v175, v175, v94, v95
	v_max3_f32 v174, v174, v112, v113
	v_max3_f32 v175, v175, v96, v97
	v_max_f32_e32 v174, v174, v175
	v_cndmask_b32_e64 v174, v194, v174, s[4:5]
	v_mov_b32_e32 v175, v174
	s_nop 1
	v_permlane32_swap_b32_e32 v174, v175
	v_max_f32_e32 v174, v174, v175
	v_mul_f32_e32 v174, 0x3e0293ee, v174
	v_cmp_gt_f32_e32 vcc, v174, v2
	s_nop 1
	v_cndmask_b32_e32 v218, v217, v174, vcc
	v_sub_f32_e32 v175, v217, v218
	v_exp_f32_e32 v2, v175
	s_nop 0
	v_cmp_neq_f32_e32 vcc, 1.0, v2
	s_cbranch_vccz .Lfast_slc_norescale
	v_pk_mul_f32 v[80:81], v[80:81], v[2:3] op_sel_hi:[1,0]
	v_pk_mul_f32 v[78:79], v[78:79], v[2:3] op_sel_hi:[1,0]
	v_pk_mul_f32 v[76:77], v[76:77], v[2:3] op_sel_hi:[1,0]
	v_pk_mul_f32 v[74:75], v[74:75], v[2:3] op_sel_hi:[1,0]
	v_pk_mul_f32 v[72:73], v[72:73], v[2:3] op_sel_hi:[1,0]
	v_pk_mul_f32 v[70:71], v[70:71], v[2:3] op_sel_hi:[1,0]
	v_pk_mul_f32 v[68:69], v[68:69], v[2:3] op_sel_hi:[1,0]
	v_pk_mul_f32 v[66:67], v[66:67], v[2:3] op_sel_hi:[1,0]
	v_pk_mul_f32 v[64:65], v[64:65], v[2:3] op_sel_hi:[1,0]
	v_pk_mul_f32 v[62:63], v[62:63], v[2:3] op_sel_hi:[1,0]
	v_pk_mul_f32 v[60:61], v[60:61], v[2:3] op_sel_hi:[1,0]
	v_pk_mul_f32 v[58:59], v[58:59], v[2:3] op_sel_hi:[1,0]
	v_pk_mul_f32 v[56:57], v[56:57], v[2:3] op_sel_hi:[1,0]
	v_pk_mul_f32 v[54:55], v[54:55], v[2:3] op_sel_hi:[1,0]
	v_pk_mul_f32 v[52:53], v[52:53], v[2:3] op_sel_hi:[1,0]
	v_pk_mul_f32 v[50:51], v[50:51], v[2:3] op_sel_hi:[1,0]
	v_pk_mul_f32 v[48:49], v[48:49], v[2:3] op_sel_hi:[1,0]
	v_pk_mul_f32 v[46:47], v[46:47], v[2:3] op_sel_hi:[1,0]
	v_pk_mul_f32 v[44:45], v[44:45], v[2:3] op_sel_hi:[1,0]
	v_pk_mul_f32 v[42:43], v[42:43], v[2:3] op_sel_hi:[1,0]
	v_pk_mul_f32 v[40:41], v[40:41], v[2:3] op_sel_hi:[1,0]
	v_pk_mul_f32 v[38:39], v[38:39], v[2:3] op_sel_hi:[1,0]
	v_pk_mul_f32 v[36:37], v[36:37], v[2:3] op_sel_hi:[1,0]
	v_pk_mul_f32 v[34:35], v[34:35], v[2:3] op_sel_hi:[1,0]
	v_pk_mul_f32 v[32:33], v[32:33], v[2:3] op_sel_hi:[1,0]
	v_pk_mul_f32 v[30:31], v[30:31], v[2:3] op_sel_hi:[1,0]
	v_pk_mul_f32 v[28:29], v[28:29], v[2:3] op_sel_hi:[1,0]
	v_pk_mul_f32 v[26:27], v[26:27], v[2:3] op_sel_hi:[1,0]
	v_pk_mul_f32 v[24:25], v[24:25], v[2:3] op_sel_hi:[1,0]
	v_pk_mul_f32 v[22:23], v[22:23], v[2:3] op_sel_hi:[1,0]
	v_pk_mul_f32 v[20:21], v[20:21], v[2:3] op_sel_hi:[1,0]
	v_pk_mul_f32 v[18:19], v[18:19], v[2:3] op_sel_hi:[1,0]
; template <int MODE, int DK, bool PASS2> ...
;     ...
;                     if (MODE == M_SLC) nm = selbit ? nm : -__builtin_inff();
;                     float ps0 = 0.f, ps1 = 0.f;
; #pragma unroll
;                     for (int r = 0; r < 16; ++r) {
;                         s0[r] = fexp2(__builtin_fmaf(s0[r], sl2, nm)); s1[r] = fexp2(__builtin_fmaf(s1[r], sl2, nm));
;                         ps0 += s0[r]; ps1 += s1[r];
;                     }
;                     l_run = l_run * alpha + (ps0 + ps1);
;                     if (__builtin_amdgcn_ballot_w64(alpha != 1.0f) != 0ull) {
; #pragma unroll
;                         for (int db = 0; db < 4; ++db)
; #pragma unroll
;                             for (int r = 0; r < 16; ++r) O[db][r] *= alpha;
;                     }
;                 } else {
; #pragma unroll
;                     for (int r = 0; r < 16; ++r) { s0[r] *= sl2; s1[r] *= sl2; }
;                     if (need_bias || need_causal || need_win) {
; #pragma unroll
;                         for (int i = 0; i < 32; ++i) {
;                             const int s = kv0 + (i >> 3) * 16 + 8 * g + (i & 7);
;                             const int dist = t_lane - ((MODE == M_CMP) ? 16 * s + 31 : s);
;                             float v = (i < 16) ? s0[i & 15] : s1[i & 15];
;                             if (need_bias) { const int di = dist < 0 ? 0 : (dist > 128 ? 128 : dist); v += tb[di]; }
;                             bool msk = dist < 0;
;                             if (MODE == M_WIN) msk = msk || dist >= 512;
;                             if (msk) v = NEG;
;                             if (i < 16) s0[i & 15] = v; else s1[i & 15] = v;
;                             if ((i & 7) == 7) __builtin_amdgcn_sched_barrier(0);
;                         }
;                     }
;                     if (MODE == M_SLC) {
;                         if (!selbit) {
; #pragma unroll
;                             for (int r = 0; r < 16; ++r) { s0[r] = NEG; s1[r] = NEG; }
;                         }
;                     }
;                     if (!PASS2) {
;                         float mx = fmaxf(s0[0], s1[0]);
; #pragma unroll
;                         for (int r = 1; r < 16; ++r) mx = fmax3(mx, s0[r], s1[r]);
;                         mx = xhalf_max(mx);
;                         const float mn = (mx > m_run + 8.0f) ? mx : m_run;
.Lfast_slc_norescale:
	v_cndmask_b32_e64 v191, v195, -v218, s[4:5]
	v_fmamk_f32 v12, v98, 0x3e0293ee, v191
	v_fmamk_f32 v13, v99, 0x3e0293ee, v191
	v_exp_f32_e32 v4, v12
	v_exp_f32_e32 v5, v13
	v_fmamk_f32 v14, v100, 0x3e0293ee, v191
	v_fmamk_f32 v15, v101, 0x3e0293ee, v191
	v_exp_f32_e32 v6, v14
	v_exp_f32_e32 v7, v15
	v_add_f32_e32 v16, v4, v5
	v_fmamk_f32 v12, v102, 0x3e0293ee, v191
	v_fmamk_f32 v13, v103, 0x3e0293ee, v191
	v_exp_f32_e32 v8, v12
	v_exp_f32_e32 v9, v13
	v_cvt_pk_bf16_f32 v98, v4, v5
	v_add_f32_e32 v16, v16, v6
	v_fmamk_f32 v14, v104, 0x3e0293ee, v191
	v_add_f32_e32 v16, v16, v7
	v_fmamk_f32 v15, v105, 0x3e0293ee, v191
	v_exp_f32_e32 v10, v14
	v_exp_f32_e32 v11, v15
	v_cvt_pk_bf16_f32 v99, v6, v7
	v_add_f32_e32 v16, v16, v8
	v_add_f32_e32 v16, v16, v9
	v_cvt_pk_bf16_f32 v100, v8, v9
	v_add_f32_e32 v16, v16, v10
	v_add_f32_e32 v16, v16, v11
	v_cvt_pk_bf16_f32 v101, v10, v11
	v_fmamk_f32 v12, v106, 0x3e0293ee, v191
	v_fmamk_f32 v13, v107, 0x3e0293ee, v191
	s_waitcnt lgkmcnt(5)
	v_mfma_f32_32x32x16_bf16 v[66:81], v[222:225], v[98:101], v[66:81]
	v_exp_f32_e32 v4, v12
	v_exp_f32_e32 v5, v13
	v_fmamk_f32 v14, v108, 0x3e0293ee, v191
	v_fmamk_f32 v15, v109, 0x3e0293ee, v191
	v_exp_f32_e32 v6, v14
	v_exp_f32_e32 v7, v15
	s_waitcnt lgkmcnt(4)
	v_mfma_f32_32x32x16_bf16 v[50:65], v[226:229], v[98:101], v[50:65]
	ds_read_b128 v[222:225], v220 offset:44064
	v_add_f32_e32 v16, v16, v4
	v_fmamk_f32 v12, v110, 0x3e0293ee, v191
	v_add_f32_e32 v16, v16, v5
	v_fmamk_f32 v13, v111, 0x3e0293ee, v191
	v_exp_f32_e32 v8, v12
	v_exp_f32_e32 v9, v13
	s_waitcnt lgkmcnt(4)
	v_mfma_f32_32x32x16_bf16 v[34:49], v[230:233], v[98:101], v[34:49]
	ds_read_b128 v[226:229], v220 offset:48672
	v_cvt_pk_bf16_f32 v106, v4, v5
	v_add_f32_e32 v16, v16, v6
	v_fmamk_f32 v14, v112, 0x3e0293ee, v191
	v_add_f32_e32 v16, v16, v7
	v_fmamk_f32 v15, v113, 0x3e0293ee, v191
	v_exp_f32_e32 v10, v14
	s_waitcnt lgkmcnt(4)
	v_mfma_f32_32x32x16_bf16 v[18:33], v[234:237], v[98:101], v[18:33]
	ds_read_b128 v[230:233], v220 offset:34880
	v_exp_f32_e32 v11, v15
	v_cvt_pk_bf16_f32 v107, v6, v7
	v_add_f32_e32 v16, v16, v8
	v_add_f32_e32 v16, v16, v9
	v_cvt_pk_bf16_f32 v108, v8, v9
	v_add_f32_e32 v16, v16, v10
	v_add_f32_e32 v16, v16, v11
	v_cvt_pk_bf16_f32 v109, v10, v11
	v_fmamk_f32 v12, v82, 0x3e0293ee, v191
	v_fmamk_f32 v13, v83, 0x3e0293ee, v191
	s_waitcnt lgkmcnt(4)
	v_mfma_f32_32x32x16_bf16 v[66:81], v[238:241], v[106:109], v[66:81]
	ds_read_b128 v[234:237], v220 offset:39488
	v_exp_f32_e32 v4, v12
	v_exp_f32_e32 v5, v13
	v_fmamk_f32 v14, v84, 0x3e0293ee, v191
	v_fmamk_f32 v15, v85, 0x3e0293ee, v191
	v_exp_f32_e32 v6, v14
	v_exp_f32_e32 v7, v15
	s_waitcnt lgkmcnt(4)
	v_mfma_f32_32x32x16_bf16 v[50:65], v[242:245], v[106:109], v[50:65]
	ds_read_b128 v[238:241], v220 offset:44096
	v_add_f32_e32 v17, v4, v5
	v_fmamk_f32 v12, v86, 0x3e0293ee, v191
	v_fmamk_f32 v13, v87, 0x3e0293ee, v191
	v_exp_f32_e32 v8, v12
	v_exp_f32_e32 v9, v13
	v_cvt_pk_bf16_f32 v82, v4, v5
	s_waitcnt lgkmcnt(4)
	v_mfma_f32_32x32x16_bf16 v[34:49], v[222:225], v[106:109], v[34:49]
	ds_read_b128 v[242:245], v220 offset:48704
	v_add_f32_e32 v17, v17, v6
	v_fmamk_f32 v14, v88, 0x3e0293ee, v191
	v_add_f32_e32 v17, v17, v7
	v_fmamk_f32 v15, v89, 0x3e0293ee, v191
	v_exp_f32_e32 v10, v14
	v_exp_f32_e32 v11, v15
	s_waitcnt lgkmcnt(4)
	v_mfma_f32_32x32x16_bf16 v[18:33], v[226:229], v[106:109], v[18:33]
	ds_read_b128 v[222:225], v220 offset:34912
	v_cvt_pk_bf16_f32 v83, v6, v7
	v_add_f32_e32 v17, v17, v8
	v_add_f32_e32 v17, v17, v9
	v_cvt_pk_bf16_f32 v84, v8, v9
	v_add_f32_e32 v17, v17, v10
	v_add_f32_e32 v17, v17, v11
	v_cvt_pk_bf16_f32 v85, v10, v11
	v_fmamk_f32 v12, v90, 0x3e0293ee, v191
	v_fmamk_f32 v13, v91, 0x3e0293ee, v191
	s_waitcnt lgkmcnt(4)
	v_mfma_f32_32x32x16_bf16 v[66:81], v[230:233], v[82:85], v[66:81]
	ds_read_b128 v[226:229], v220 offset:39520
	v_exp_f32_e32 v4, v12
	v_exp_f32_e32 v5, v13
	v_fmamk_f32 v14, v92, 0x3e0293ee, v191
	v_fmamk_f32 v15, v93, 0x3e0293ee, v191
	v_exp_f32_e32 v6, v14
	v_exp_f32_e32 v7, v15
	s_waitcnt lgkmcnt(4)
	v_mfma_f32_32x32x16_bf16 v[50:65], v[234:237], v[82:85], v[50:65]
	ds_read_b128 v[230:233], v220 offset:44128
	v_add_f32_e32 v17, v17, v4
	v_fmamk_f32 v12, v94, 0x3e0293ee, v191
	v_add_f32_e32 v17, v17, v5
	v_fmamk_f32 v13, v95, 0x3e0293ee, v191
	v_exp_f32_e32 v8, v12
	v_exp_f32_e32 v9, v13
	s_waitcnt lgkmcnt(4)
	v_mfma_f32_32x32x16_bf16 v[34:49], v[238:241], v[82:85], v[34:49]
	ds_read_b128 v[234:237], v220 offset:48736
	v_cvt_pk_bf16_f32 v90, v4, v5
	v_add_f32_e32 v17, v17, v6
	v_fmamk_f32 v14, v96, 0x3e0293ee, v191
	v_add_f32_e32 v17, v17, v7
	v_fmamk_f32 v15, v97, 0x3e0293ee, v191
	v_exp_f32_e32 v10, v14
	s_waitcnt lgkmcnt(4)
	v_mfma_f32_32x32x16_bf16 v[18:33], v[242:245], v[82:85], v[18:33]
	v_exp_f32_e32 v11, v15
	v_cvt_pk_bf16_f32 v91, v6, v7
	v_add_f32_e32 v17, v17, v8
	v_add_f32_e32 v17, v17, v9
	v_cvt_pk_bf16_f32 v92, v8, v9
	v_add_f32_e32 v17, v17, v10
	v_add_f32_e32 v17, v17, v11
	v_cvt_pk_bf16_f32 v93, v10, v11
	v_add_f32_e32 v219, v16, v17
	s_waitcnt lgkmcnt(3)
	v_mfma_f32_32x32x16_bf16 v[66:81], v[222:225], v[90:93], v[66:81]
	v_fmac_f32_e32 v219, v216, v2
	s_waitcnt lgkmcnt(2)
	v_mfma_f32_32x32x16_bf16 v[50:65], v[226:229], v[90:93], v[50:65]
	s_waitcnt lgkmcnt(1)
	v_mfma_f32_32x32x16_bf16 v[34:49], v[230:233], v[90:93], v[34:49]
	s_waitcnt lgkmcnt(0)
	v_mfma_f32_32x32x16_bf16 v[18:33], v[234:237], v[90:93], v[18:33]
	s_setprio 0
	s_branch .Lpostpv_slc
